# seam conversion: transposed LDS reads issued 16 at a time with counted lgkmcnt instead of 8 + full wait
# speedup vs baseline: 1.0213x; 1.0016x over previous
.Lmy_cv0_sd:
	s_lshl_b32 s70, vcc_hi, 17
	s_lshl_b32 s71, vcc_lo, 7
	s_add_i32 s70, s70, s71
	s_add_u32 s70, s70, 0x1a00000
	s_add_u32 s70, s26, s70
	s_addc_u32 s71, s27, 0
	s_waitcnt lgkmcnt(0)
	ds_read_b32 v160, v3 offset:0
	ds_read_b32 v161, v3 offset:132
	ds_read_b32 v162, v3 offset:264
	ds_read_b32 v163, v3 offset:396
	ds_read_b32 v164, v3 offset:528
	ds_read_b32 v165, v3 offset:660
	ds_read_b32 v166, v3 offset:792
	ds_read_b32 v167, v3 offset:924
	ds_read_b32 v168, v3 offset:32
	ds_read_b32 v169, v3 offset:164
	ds_read_b32 v170, v3 offset:296
	ds_read_b32 v171, v3 offset:428
	ds_read_b32 v172, v3 offset:560
	ds_read_b32 v173, v3 offset:692
	ds_read_b32 v174, v3 offset:824
	ds_read_b32 v175, v3 offset:956
	s_waitcnt lgkmcnt(8)
	v_mul_f32_e32 v160, v160, v144
	v_mul_f32_e32 v161, v161, v145
	v_mul_f32_e32 v162, v162, v146
	v_mul_f32_e32 v163, v163, v147
	v_mul_f32_e32 v164, v164, v148
	v_mul_f32_e32 v165, v165, v149
	v_mul_f32_e32 v166, v166, v150
	v_mul_f32_e32 v167, v167, v151
	v_cvt_pk_bf16_f32 v192, v160, v161
	v_cvt_pk_bf16_f32 v193, v162, v163
	v_cvt_pk_bf16_f32 v194, v164, v165
	v_cvt_pk_bf16_f32 v195, v166, v167
	v_mov_b32_e32 v9, v4
	global_store_dwordx4 v9, v[192:195], s[70:71]
	s_waitcnt lgkmcnt(0)
	v_mul_f32_e32 v168, v168, v144
	v_mul_f32_e32 v169, v169, v145
	v_mul_f32_e32 v170, v170, v146
	v_mul_f32_e32 v171, v171, v147
	v_mul_f32_e32 v172, v172, v148
	v_mul_f32_e32 v173, v173, v149
	v_mul_f32_e32 v174, v174, v150
	v_mul_f32_e32 v175, v175, v151
	v_cvt_pk_bf16_f32 v196, v168, v169
	v_cvt_pk_bf16_f32 v197, v170, v171
	v_cvt_pk_bf16_f32 v198, v172, v173
	v_cvt_pk_bf16_f32 v199, v174, v175
	v_add_u32_e32 v9, 0x8000, v9
	global_store_dwordx4 v9, v[196:199], s[70:71]
	ds_read_b32 v176, v3 offset:64
	ds_read_b32 v177, v3 offset:196
	ds_read_b32 v178, v3 offset:328
	ds_read_b32 v179, v3 offset:460
	ds_read_b32 v180, v3 offset:592
	ds_read_b32 v181, v3 offset:724
	ds_read_b32 v182, v3 offset:856
	ds_read_b32 v183, v3 offset:988
	ds_read_b32 v184, v3 offset:96
	ds_read_b32 v185, v3 offset:228
	ds_read_b32 v186, v3 offset:360
	ds_read_b32 v187, v3 offset:492
	ds_read_b32 v188, v3 offset:624
	ds_read_b32 v189, v3 offset:756
	ds_read_b32 v190, v3 offset:888
	ds_read_b32 v191, v3 offset:1020
	s_waitcnt lgkmcnt(8)
	v_mul_f32_e32 v176, v176, v144
	v_mul_f32_e32 v177, v177, v145
	v_mul_f32_e32 v178, v178, v146
	v_mul_f32_e32 v179, v179, v147
	v_mul_f32_e32 v180, v180, v148
	v_mul_f32_e32 v181, v181, v149
	v_mul_f32_e32 v182, v182, v150
	v_mul_f32_e32 v183, v183, v151
	v_cvt_pk_bf16_f32 v200, v176, v177
	v_cvt_pk_bf16_f32 v201, v178, v179
	v_cvt_pk_bf16_f32 v202, v180, v181
	v_cvt_pk_bf16_f32 v203, v182, v183
	v_add_u32_e32 v9, 0x8000, v9
	global_store_dwordx4 v9, v[200:203], s[70:71]
	s_waitcnt lgkmcnt(0)
	v_mul_f32_e32 v184, v184, v144
	v_mul_f32_e32 v185, v185, v145
	v_mul_f32_e32 v186, v186, v146
	v_mul_f32_e32 v187, v187, v147
	v_mul_f32_e32 v188, v188, v148
	v_mul_f32_e32 v189, v189, v149
	v_mul_f32_e32 v190, v190, v150
	v_mul_f32_e32 v191, v191, v151
	v_cvt_pk_bf16_f32 v204, v184, v185
	v_cvt_pk_bf16_f32 v205, v186, v187
	v_cvt_pk_bf16_f32 v206, v188, v189
	v_cvt_pk_bf16_f32 v207, v190, v191
	v_add_u32_e32 v9, 0x8000, v9
	global_store_dwordx4 v9, v[204:207], s[70:71]
	s_waitcnt vmcnt(34)
	s_waitcnt lgkmcnt(0)
	ds_write_b32 v2, v32 offset:0
	ds_write_b32 v2, v33 offset:264
	ds_write_b32 v2, v34 offset:528
	ds_write_b32 v2, v35 offset:792
	ds_write_b32 v2, v36 offset:1056
	ds_write_b32 v2, v37 offset:1320
	ds_write_b32 v2, v38 offset:1584
	ds_write_b32 v2, v39 offset:1848
	ds_write_b32 v2, v40 offset:2112
	ds_write_b32 v2, v41 offset:2376
	ds_write_b32 v2, v42 offset:2640
	ds_write_b32 v2, v43 offset:2904
	ds_write_b32 v2, v44 offset:3168
	ds_write_b32 v2, v45 offset:3432
	ds_write_b32 v2, v46 offset:3696
	ds_write_b32 v2, v47 offset:3960
	ds_write_b32 v2, v48 offset:4224
	ds_write_b32 v2, v49 offset:4488
	ds_write_b32 v2, v50 offset:4752
	ds_write_b32 v2, v51 offset:5016
	ds_write_b32 v2, v52 offset:5280
	ds_write_b32 v2, v53 offset:5544
	ds_write_b32 v2, v54 offset:5808
	ds_write_b32 v2, v55 offset:6072
	ds_write_b32 v2, v56 offset:6336
	ds_write_b32 v2, v57 offset:6600
	ds_write_b32 v2, v58 offset:6864
	ds_write_b32 v2, v59 offset:7128
	ds_write_b32 v2, v60 offset:7392
	ds_write_b32 v2, v61 offset:7656
	ds_write_b32 v2, v62 offset:7920
	ds_write_b32 v2, v63 offset:8184
	s_lshr_b32 s70, s5, 2
	s_lshl_b32 s70, s70, 8
	s_and_b32 s71, s5, 3
	s_lshl_b32 s71, s71, 5
	s_add_i32 s70, s70, s71
	s_add_i32 s70, s70, s54
	s_lshl_b32 s70, s70, 12
	s_lshl_b32 s71, s4, 7
	s_add_i32 s70, s70, s71
	s_add_u32 s70, s70, 0x2200000
	s_add_u32 s70, s26, s70
	s_addc_u32 s71, s27, 0
	s_waitcnt lgkmcnt(0)
	ds_read_b32 v160, v3 offset:0
	ds_read_b32 v161, v3 offset:132
	ds_read_b32 v162, v3 offset:264
	ds_read_b32 v163, v3 offset:396
	ds_read_b32 v164, v3 offset:528
	ds_read_b32 v165, v3 offset:660
	ds_read_b32 v166, v3 offset:792
	ds_read_b32 v167, v3 offset:924
	ds_read_b32 v168, v3 offset:32
	ds_read_b32 v169, v3 offset:164
	ds_read_b32 v170, v3 offset:296
	ds_read_b32 v171, v3 offset:428
	ds_read_b32 v172, v3 offset:560
	ds_read_b32 v173, v3 offset:692
	ds_read_b32 v174, v3 offset:824
	ds_read_b32 v175, v3 offset:956
	s_waitcnt lgkmcnt(8)
	v_mul_f32_e32 v160, v160, v96
	v_mul_f32_e32 v161, v161, v97
	v_mul_f32_e32 v162, v162, v98
	v_mul_f32_e32 v163, v163, v99
	v_mul_f32_e32 v164, v164, v100
	v_mul_f32_e32 v165, v165, v101
	v_mul_f32_e32 v166, v166, v102
	v_mul_f32_e32 v167, v167, v103
	v_cvt_pk_bf16_f32 v192, v160, v161
	v_cvt_pk_bf16_f32 v193, v162, v163
	v_cvt_pk_bf16_f32 v194, v164, v165
	v_cvt_pk_bf16_f32 v195, v166, v167
	v_mov_b32_e32 v9, v4
	global_store_dwordx4 v9, v[192:195], s[70:71]
	s_waitcnt lgkmcnt(0)
	v_mul_f32_e32 v168, v168, v96
	v_mul_f32_e32 v169, v169, v97
	v_mul_f32_e32 v170, v170, v98
	v_mul_f32_e32 v171, v171, v99
	v_mul_f32_e32 v172, v172, v100
	v_mul_f32_e32 v173, v173, v101
	v_mul_f32_e32 v174, v174, v102
	v_mul_f32_e32 v175, v175, v103
	v_cvt_pk_bf16_f32 v196, v168, v169
	v_cvt_pk_bf16_f32 v197, v170, v171
	v_cvt_pk_bf16_f32 v198, v172, v173
	v_cvt_pk_bf16_f32 v199, v174, v175
	v_add_u32_e32 v9, 0x8000, v9
	global_store_dwordx4 v9, v[196:199], s[70:71]
	ds_read_b32 v176, v3 offset:64
	ds_read_b32 v177, v3 offset:196
	ds_read_b32 v178, v3 offset:328
	ds_read_b32 v179, v3 offset:460
	ds_read_b32 v180, v3 offset:592
	ds_read_b32 v181, v3 offset:724
	ds_read_b32 v182, v3 offset:856
	ds_read_b32 v183, v3 offset:988
	ds_read_b32 v184, v3 offset:96
	ds_read_b32 v185, v3 offset:228
	ds_read_b32 v186, v3 offset:360
	ds_read_b32 v187, v3 offset:492
	ds_read_b32 v188, v3 offset:624
	ds_read_b32 v189, v3 offset:756
	ds_read_b32 v190, v3 offset:888
	ds_read_b32 v191, v3 offset:1020
	s_waitcnt lgkmcnt(8)
	v_mul_f32_e32 v176, v176, v96
	v_mul_f32_e32 v177, v177, v97
	v_mul_f32_e32 v178, v178, v98
	v_mul_f32_e32 v179, v179, v99
	v_mul_f32_e32 v180, v180, v100
	v_mul_f32_e32 v181, v181, v101
	v_mul_f32_e32 v182, v182, v102
	v_mul_f32_e32 v183, v183, v103
	v_cvt_pk_bf16_f32 v200, v176, v177
	v_cvt_pk_bf16_f32 v201, v178, v179
	v_cvt_pk_bf16_f32 v202, v180, v181
	v_cvt_pk_bf16_f32 v203, v182, v183
	v_add_u32_e32 v9, 0x8000, v9
	global_store_dwordx4 v9, v[200:203], s[70:71]
	s_waitcnt lgkmcnt(0)
	v_mul_f32_e32 v184, v184, v96
	v_mul_f32_e32 v185, v185, v97
	v_mul_f32_e32 v186, v186, v98
	v_mul_f32_e32 v187, v187, v99
	v_mul_f32_e32 v188, v188, v100
	v_mul_f32_e32 v189, v189, v101
	v_mul_f32_e32 v190, v190, v102
	v_mul_f32_e32 v191, v191, v103
	v_cvt_pk_bf16_f32 v204, v184, v185
	v_cvt_pk_bf16_f32 v205, v186, v187
	v_cvt_pk_bf16_f32 v206, v188, v189
	v_cvt_pk_bf16_f32 v207, v190, v191
	v_add_u32_e32 v9, 0x8000, v9
	global_store_dwordx4 v9, v[204:207], s[70:71]
	s_waitcnt vmcnt(0)
	s_waitcnt lgkmcnt(0)
	ds_write_b32 v2, v64 offset:0
	ds_write_b32 v2, v65 offset:264
	ds_write_b32 v2, v66 offset:528
	ds_write_b32 v2, v67 offset:792
	ds_write_b32 v2, v68 offset:1056
	ds_write_b32 v2, v69 offset:1320
	ds_write_b32 v2, v70 offset:1584
	ds_write_b32 v2, v71 offset:1848
	ds_write_b32 v2, v72 offset:2112
	ds_write_b32 v2, v73 offset:2376
	ds_write_b32 v2, v74 offset:2640
	ds_write_b32 v2, v75 offset:2904
	ds_write_b32 v2, v76 offset:3168
	ds_write_b32 v2, v77 offset:3432
	ds_write_b32 v2, v78 offset:3696
	ds_write_b32 v2, v79 offset:3960
	ds_write_b32 v2, v80 offset:4224
	ds_write_b32 v2, v81 offset:4488
	ds_write_b32 v2, v82 offset:4752
	ds_write_b32 v2, v83 offset:5016
	ds_write_b32 v2, v84 offset:5280
	ds_write_b32 v2, v85 offset:5544
	ds_write_b32 v2, v86 offset:5808
	ds_write_b32 v2, v87 offset:6072
	ds_write_b32 v2, v88 offset:6336
	ds_write_b32 v2, v89 offset:6600
	ds_write_b32 v2, v90 offset:6864
	ds_write_b32 v2, v91 offset:7128
	ds_write_b32 v2, v92 offset:7392
	ds_write_b32 v2, v93 offset:7656
	ds_write_b32 v2, v94 offset:7920
	ds_write_b32 v2, v95 offset:8184
	s_lshr_b32 s70, s67, 2
	s_lshl_b32 s70, s70, 8
	s_and_b32 s71, s67, 3
	s_lshl_b32 s71, s71, 5
	s_add_i32 s70, s70, s71
	s_add_i32 s70, s70, s40
	s_lshl_b32 s70, s70, 12
	s_lshl_b32 s71, s55, 7
	s_add_i32 s70, s70, s71
	s_add_u32 s70, s70, 0x2200000
	s_add_u32 s70, s26, s70
	s_addc_u32 s71, s27, 0
	s_waitcnt lgkmcnt(0)
	ds_read_b32 v160, v3 offset:0
	ds_read_b32 v161, v3 offset:132
	ds_read_b32 v162, v3 offset:264
	ds_read_b32 v163, v3 offset:396
	ds_read_b32 v164, v3 offset:528
	ds_read_b32 v165, v3 offset:660
	ds_read_b32 v166, v3 offset:792
	ds_read_b32 v167, v3 offset:924
	ds_read_b32 v168, v3 offset:32
	ds_read_b32 v169, v3 offset:164
	ds_read_b32 v170, v3 offset:296
	ds_read_b32 v171, v3 offset:428
	ds_read_b32 v172, v3 offset:560
	ds_read_b32 v173, v3 offset:692
	ds_read_b32 v174, v3 offset:824
	ds_read_b32 v175, v3 offset:956
	s_waitcnt lgkmcnt(8)
	v_mul_f32_e32 v160, v160, v104
	v_mul_f32_e32 v161, v161, v105
	v_mul_f32_e32 v162, v162, v106
	v_mul_f32_e32 v163, v163, v107
	v_mul_f32_e32 v164, v164, v108
	v_mul_f32_e32 v165, v165, v109
	v_mul_f32_e32 v166, v166, v110
	v_mul_f32_e32 v167, v167, v111
	v_cvt_pk_bf16_f32 v192, v160, v161
	v_cvt_pk_bf16_f32 v193, v162, v163
	v_cvt_pk_bf16_f32 v194, v164, v165
	v_cvt_pk_bf16_f32 v195, v166, v167
	v_mov_b32_e32 v9, v4
	global_store_dwordx4 v9, v[192:195], s[70:71]
	s_waitcnt lgkmcnt(0)
	v_mul_f32_e32 v168, v168, v104
	v_mul_f32_e32 v169, v169, v105
	v_mul_f32_e32 v170, v170, v106
	v_mul_f32_e32 v171, v171, v107
	v_mul_f32_e32 v172, v172, v108
	v_mul_f32_e32 v173, v173, v109
	v_mul_f32_e32 v174, v174, v110
	v_mul_f32_e32 v175, v175, v111
	v_cvt_pk_bf16_f32 v196, v168, v169
	v_cvt_pk_bf16_f32 v197, v170, v171
	v_cvt_pk_bf16_f32 v198, v172, v173
	v_cvt_pk_bf16_f32 v199, v174, v175
	v_add_u32_e32 v9, 0x8000, v9
	global_store_dwordx4 v9, v[196:199], s[70:71]
	ds_read_b32 v176, v3 offset:64
	ds_read_b32 v177, v3 offset:196
	ds_read_b32 v178, v3 offset:328
	ds_read_b32 v179, v3 offset:460
	ds_read_b32 v180, v3 offset:592
	ds_read_b32 v181, v3 offset:724
	ds_read_b32 v182, v3 offset:856
	ds_read_b32 v183, v3 offset:988
	ds_read_b32 v184, v3 offset:96
	ds_read_b32 v185, v3 offset:228
	ds_read_b32 v186, v3 offset:360
	ds_read_b32 v187, v3 offset:492
	ds_read_b32 v188, v3 offset:624
	ds_read_b32 v189, v3 offset:756
	ds_read_b32 v190, v3 offset:888
	ds_read_b32 v191, v3 offset:1020
	s_waitcnt lgkmcnt(8)
	v_mul_f32_e32 v176, v176, v104
	v_mul_f32_e32 v177, v177, v105
	v_mul_f32_e32 v178, v178, v106
	v_mul_f32_e32 v179, v179, v107
	v_mul_f32_e32 v180, v180, v108
	v_mul_f32_e32 v181, v181, v109
	v_mul_f32_e32 v182, v182, v110
	v_mul_f32_e32 v183, v183, v111
	v_cvt_pk_bf16_f32 v200, v176, v177
	v_cvt_pk_bf16_f32 v201, v178, v179
	v_cvt_pk_bf16_f32 v202, v180, v181
	v_cvt_pk_bf16_f32 v203, v182, v183
	v_add_u32_e32 v9, 0x8000, v9
	global_store_dwordx4 v9, v[200:203], s[70:71]
	s_waitcnt lgkmcnt(0)
	v_mul_f32_e32 v184, v184, v104
	v_mul_f32_e32 v185, v185, v105
	v_mul_f32_e32 v186, v186, v106
	v_mul_f32_e32 v187, v187, v107
	v_mul_f32_e32 v188, v188, v108
	v_mul_f32_e32 v189, v189, v109
	v_mul_f32_e32 v190, v190, v110
	v_mul_f32_e32 v191, v191, v111
	v_cvt_pk_bf16_f32 v204, v184, v185
	v_cvt_pk_bf16_f32 v205, v186, v187
	v_cvt_pk_bf16_f32 v206, v188, v189
	v_cvt_pk_bf16_f32 v207, v190, v191
	v_add_u32_e32 v9, 0x8000, v9
	global_store_dwordx4 v9, v[204:207], s[70:71]
	s_waitcnt vmcnt(0) lgkmcnt(0)

.Lmy_cv1_no3a:
	s_add_i32 s66, s3, 4096
	s_cmpk_ge_u32 s66, 0x1600
	s_cselect_b32 s68, s64, s62
	s_cselect_b32 s69, s65, s63
	s_cselect_b32 s54, 128, 0
	s_cselect_b32 s41, 0x1600, 0
	s_sub_u32 s41, s66, s41
	s_mul_hi_u32 s4, s41, 0xba2e8ba3
	s_lshr_b32 s4, s4, 7
	s_mul_i32 s70, s4, 0xb0
	s_sub_u32 s5, s41, s70
	s_mul_i32 s70, s4, 0x160000
	s_lshl_b32 s71, s5, 7
	s_add_u32 s68, s68, s70
	s_addc_u32 s69, s69, 0
	s_add_u32 s68, s68, s71
	s_addc_u32 s69, s69, 0
	v_mov_b32_e32 v1, v0
	global_load_dword v32, v1, s[68:69] nt
	v_add_u32_e32 v1, 0xb000, v1
	global_load_dword v33, v1, s[68:69] nt
	v_add_u32_e32 v1, 0xb000, v1
	global_load_dword v34, v1, s[68:69] nt
	v_add_u32_e32 v1, 0xb000, v1
	global_load_dword v35, v1, s[68:69] nt
	v_add_u32_e32 v1, 0xb000, v1
	global_load_dword v36, v1, s[68:69] nt
	v_add_u32_e32 v1, 0xb000, v1
	global_load_dword v37, v1, s[68:69] nt
	v_add_u32_e32 v1, 0xb000, v1
	global_load_dword v38, v1, s[68:69] nt
	v_add_u32_e32 v1, 0xb000, v1
	global_load_dword v39, v1, s[68:69] nt
	v_add_u32_e32 v1, 0xb000, v1
	global_load_dword v40, v1, s[68:69] nt
	v_add_u32_e32 v1, 0xb000, v1
	global_load_dword v41, v1, s[68:69] nt
	v_add_u32_e32 v1, 0xb000, v1
	global_load_dword v42, v1, s[68:69] nt
	v_add_u32_e32 v1, 0xb000, v1
	global_load_dword v43, v1, s[68:69] nt
	v_add_u32_e32 v1, 0xb000, v1
	global_load_dword v44, v1, s[68:69] nt
	v_add_u32_e32 v1, 0xb000, v1
	global_load_dword v45, v1, s[68:69] nt
	v_add_u32_e32 v1, 0xb000, v1
	global_load_dword v46, v1, s[68:69] nt
	v_add_u32_e32 v1, 0xb000, v1
	global_load_dword v47, v1, s[68:69] nt
	v_add_u32_e32 v1, 0xb000, v1
	global_load_dword v48, v1, s[68:69] nt
	v_add_u32_e32 v1, 0xb000, v1
	global_load_dword v49, v1, s[68:69] nt
	v_add_u32_e32 v1, 0xb000, v1
	global_load_dword v50, v1, s[68:69] nt
	v_add_u32_e32 v1, 0xb000, v1
	global_load_dword v51, v1, s[68:69] nt
	v_add_u32_e32 v1, 0xb000, v1
	global_load_dword v52, v1, s[68:69] nt
	v_add_u32_e32 v1, 0xb000, v1
	global_load_dword v53, v1, s[68:69] nt
	v_add_u32_e32 v1, 0xb000, v1
	global_load_dword v54, v1, s[68:69] nt
	v_add_u32_e32 v1, 0xb000, v1
	global_load_dword v55, v1, s[68:69] nt
	v_add_u32_e32 v1, 0xb000, v1
	global_load_dword v56, v1, s[68:69] nt
	v_add_u32_e32 v1, 0xb000, v1
	global_load_dword v57, v1, s[68:69] nt
	v_add_u32_e32 v1, 0xb000, v1
	global_load_dword v58, v1, s[68:69] nt
	v_add_u32_e32 v1, 0xb000, v1
	global_load_dword v59, v1, s[68:69] nt
	v_add_u32_e32 v1, 0xb000, v1
	global_load_dword v60, v1, s[68:69] nt
	v_add_u32_e32 v1, 0xb000, v1
	global_load_dword v61, v1, s[68:69] nt
	v_add_u32_e32 v1, 0xb000, v1
	global_load_dword v62, v1, s[68:69] nt
	v_add_u32_e32 v1, 0xb000, v1
	global_load_dword v63, v1, s[68:69] nt
	s_lshl_b32 s70, s4, 8
	s_add_u32 s70, s60, s70
	s_addc_u32 s71, s61, 0
	global_load_dwordx4 v[96:99], v5, s[70:71]
	global_load_dwordx4 v[100:103], v5, s[70:71] offset:16
	s_addk_i32 s66, 0x700
	s_cmpk_ge_u32 s66, 0x1600
	s_cselect_b32 s68, s64, s62
	s_cselect_b32 s69, s65, s63
	s_cselect_b32 s40, 128, 0
	s_cselect_b32 s41, 0x1600, 0
	s_sub_u32 s41, s66, s41
	s_mul_hi_u32 s55, s41, 0xba2e8ba3
	s_lshr_b32 s55, s55, 7
	s_mul_i32 s70, s55, 0xb0
	s_sub_u32 s67, s41, s70
	s_mul_i32 s70, s55, 0x160000
	s_lshl_b32 s71, s67, 7
	s_add_u32 s68, s68, s70
	s_addc_u32 s69, s69, 0
	s_add_u32 s68, s68, s71
	s_addc_u32 s69, s69, 0
	v_mov_b32_e32 v1, v0
	global_load_dword v64, v1, s[68:69] nt
	v_add_u32_e32 v1, 0xb000, v1
	global_load_dword v65, v1, s[68:69] nt
	v_add_u32_e32 v1, 0xb000, v1
	global_load_dword v66, v1, s[68:69] nt
	v_add_u32_e32 v1, 0xb000, v1
	global_load_dword v67, v1, s[68:69] nt
	v_add_u32_e32 v1, 0xb000, v1
	global_load_dword v68, v1, s[68:69] nt
	v_add_u32_e32 v1, 0xb000, v1
	global_load_dword v69, v1, s[68:69] nt
	v_add_u32_e32 v1, 0xb000, v1
	global_load_dword v70, v1, s[68:69] nt
	v_add_u32_e32 v1, 0xb000, v1
	global_load_dword v71, v1, s[68:69] nt
	v_add_u32_e32 v1, 0xb000, v1
	global_load_dword v72, v1, s[68:69] nt
	v_add_u32_e32 v1, 0xb000, v1
	global_load_dword v73, v1, s[68:69] nt
	v_add_u32_e32 v1, 0xb000, v1
	global_load_dword v74, v1, s[68:69] nt
	v_add_u32_e32 v1, 0xb000, v1
	global_load_dword v75, v1, s[68:69] nt
	v_add_u32_e32 v1, 0xb000, v1
	global_load_dword v76, v1, s[68:69] nt
	v_add_u32_e32 v1, 0xb000, v1
	global_load_dword v77, v1, s[68:69] nt
	v_add_u32_e32 v1, 0xb000, v1
	global_load_dword v78, v1, s[68:69] nt
	v_add_u32_e32 v1, 0xb000, v1
	global_load_dword v79, v1, s[68:69] nt
	v_add_u32_e32 v1, 0xb000, v1
	global_load_dword v80, v1, s[68:69] nt
	v_add_u32_e32 v1, 0xb000, v1
	global_load_dword v81, v1, s[68:69] nt
	v_add_u32_e32 v1, 0xb000, v1
	global_load_dword v82, v1, s[68:69] nt
	v_add_u32_e32 v1, 0xb000, v1
	global_load_dword v83, v1, s[68:69] nt
	v_add_u32_e32 v1, 0xb000, v1
	global_load_dword v84, v1, s[68:69] nt
	v_add_u32_e32 v1, 0xb000, v1
	global_load_dword v85, v1, s[68:69] nt
	v_add_u32_e32 v1, 0xb000, v1
	global_load_dword v86, v1, s[68:69] nt
	v_add_u32_e32 v1, 0xb000, v1
	global_load_dword v87, v1, s[68:69] nt
	v_add_u32_e32 v1, 0xb000, v1
	global_load_dword v88, v1, s[68:69] nt
	v_add_u32_e32 v1, 0xb000, v1
	global_load_dword v89, v1, s[68:69] nt
	v_add_u32_e32 v1, 0xb000, v1
	global_load_dword v90, v1, s[68:69] nt
	v_add_u32_e32 v1, 0xb000, v1
	global_load_dword v91, v1, s[68:69] nt
	v_add_u32_e32 v1, 0xb000, v1
	global_load_dword v92, v1, s[68:69] nt
	v_add_u32_e32 v1, 0xb000, v1
	global_load_dword v93, v1, s[68:69] nt
	v_add_u32_e32 v1, 0xb000, v1
	global_load_dword v94, v1, s[68:69] nt
	v_add_u32_e32 v1, 0xb000, v1
	global_load_dword v95, v1, s[68:69] nt
	s_lshl_b32 s70, s55, 8
	s_add_u32 s70, s60, s70
	s_addc_u32 s71, s61, 0
	global_load_dwordx4 v[104:107], v5, s[70:71]
	global_load_dwordx4 v[108:111], v5, s[70:71] offset:16
	s_cmpk_lt_u32 s3, 0x200
	s_cbranch_scc0 .Lmy_cv1_no3b
	s_waitcnt vmcnt(63)
	s_waitcnt lgkmcnt(0)
	ds_write_b32 v2, v112 offset:0
	ds_write_b32 v2, v113 offset:264
	ds_write_b32 v2, v114 offset:528
	ds_write_b32 v2, v115 offset:792
	ds_write_b32 v2, v116 offset:1056
	ds_write_b32 v2, v117 offset:1320
	ds_write_b32 v2, v118 offset:1584
	ds_write_b32 v2, v119 offset:1848
	ds_write_b32 v2, v120 offset:2112
	ds_write_b32 v2, v121 offset:2376
	ds_write_b32 v2, v122 offset:2640
	ds_write_b32 v2, v123 offset:2904
	ds_write_b32 v2, v124 offset:3168
	ds_write_b32 v2, v125 offset:3432
	ds_write_b32 v2, v126 offset:3696
	ds_write_b32 v2, v127 offset:3960
	ds_write_b32 v2, v128 offset:4224
	ds_write_b32 v2, v129 offset:4488
	ds_write_b32 v2, v130 offset:4752
	ds_write_b32 v2, v131 offset:5016
	ds_write_b32 v2, v132 offset:5280
	ds_write_b32 v2, v133 offset:5544
	ds_write_b32 v2, v134 offset:5808
	ds_write_b32 v2, v135 offset:6072
	ds_write_b32 v2, v136 offset:6336
	ds_write_b32 v2, v137 offset:6600
	ds_write_b32 v2, v138 offset:6864
	ds_write_b32 v2, v139 offset:7128
	ds_write_b32 v2, v140 offset:7392
	ds_write_b32 v2, v141 offset:7656
	ds_write_b32 v2, v142 offset:7920
	ds_write_b32 v2, v143 offset:8184
	s_lshr_b32 s70, vcc_hi, 2
	s_lshl_b32 s70, s70, 8
	s_and_b32 s71, vcc_hi, 3
	s_lshl_b32 s71, s71, 5
	s_add_i32 s70, s70, s71
	s_lshl_b32 s70, s70, 12
	s_lshl_b32 s71, vcc_lo, 7
	s_add_i32 s70, s70, s71
	s_add_u32 s70, s70, 0x2200000
	s_add_u32 s70, s26, s70
	s_addc_u32 s71, s27, 0
	s_waitcnt lgkmcnt(0)
	ds_read_b32 v160, v3 offset:0
	ds_read_b32 v161, v3 offset:132
	ds_read_b32 v162, v3 offset:264
	ds_read_b32 v163, v3 offset:396
	ds_read_b32 v164, v3 offset:528
	ds_read_b32 v165, v3 offset:660
	ds_read_b32 v166, v3 offset:792
	ds_read_b32 v167, v3 offset:924
	ds_read_b32 v168, v3 offset:32
	ds_read_b32 v169, v3 offset:164
	ds_read_b32 v170, v3 offset:296
	ds_read_b32 v171, v3 offset:428
	ds_read_b32 v172, v3 offset:560
	ds_read_b32 v173, v3 offset:692
	ds_read_b32 v174, v3 offset:824
	ds_read_b32 v175, v3 offset:956
	s_waitcnt lgkmcnt(8)
	v_mul_f32_e32 v160, v160, v144
	v_mul_f32_e32 v161, v161, v145
	v_mul_f32_e32 v162, v162, v146
	v_mul_f32_e32 v163, v163, v147
	v_mul_f32_e32 v164, v164, v148
	v_mul_f32_e32 v165, v165, v149
	v_mul_f32_e32 v166, v166, v150
	v_mul_f32_e32 v167, v167, v151
	v_cvt_pk_bf16_f32 v192, v160, v161
	v_cvt_pk_bf16_f32 v193, v162, v163
	v_cvt_pk_bf16_f32 v194, v164, v165
	v_cvt_pk_bf16_f32 v195, v166, v167
	v_mov_b32_e32 v9, v4
	global_store_dwordx4 v9, v[192:195], s[70:71]
	s_waitcnt lgkmcnt(0)
	v_mul_f32_e32 v168, v168, v144
	v_mul_f32_e32 v169, v169, v145
	v_mul_f32_e32 v170, v170, v146
	v_mul_f32_e32 v171, v171, v147
	v_mul_f32_e32 v172, v172, v148
	v_mul_f32_e32 v173, v173, v149
	v_mul_f32_e32 v174, v174, v150
	v_mul_f32_e32 v175, v175, v151
	v_cvt_pk_bf16_f32 v196, v168, v169
	v_cvt_pk_bf16_f32 v197, v170, v171
	v_cvt_pk_bf16_f32 v198, v172, v173
	v_cvt_pk_bf16_f32 v199, v174, v175
	v_add_u32_e32 v9, 0x8000, v9
	global_store_dwordx4 v9, v[196:199], s[70:71]
	ds_read_b32 v176, v3 offset:64
	ds_read_b32 v177, v3 offset:196
	ds_read_b32 v178, v3 offset:328
	ds_read_b32 v179, v3 offset:460
	ds_read_b32 v180, v3 offset:592
	ds_read_b32 v181, v3 offset:724
	ds_read_b32 v182, v3 offset:856
	ds_read_b32 v183, v3 offset:988
	ds_read_b32 v184, v3 offset:96
	ds_read_b32 v185, v3 offset:228
	ds_read_b32 v186, v3 offset:360
	ds_read_b32 v187, v3 offset:492
	ds_read_b32 v188, v3 offset:624
	ds_read_b32 v189, v3 offset:756
	ds_read_b32 v190, v3 offset:888
	ds_read_b32 v191, v3 offset:1020
	s_waitcnt lgkmcnt(8)
	v_mul_f32_e32 v176, v176, v144
	v_mul_f32_e32 v177, v177, v145
	v_mul_f32_e32 v178, v178, v146
	v_mul_f32_e32 v179, v179, v147
	v_mul_f32_e32 v180, v180, v148
	v_mul_f32_e32 v181, v181, v149
	v_mul_f32_e32 v182, v182, v150
	v_mul_f32_e32 v183, v183, v151
	v_cvt_pk_bf16_f32 v200, v176, v177
	v_cvt_pk_bf16_f32 v201, v178, v179
	v_cvt_pk_bf16_f32 v202, v180, v181
	v_cvt_pk_bf16_f32 v203, v182, v183
	v_add_u32_e32 v9, 0x8000, v9
	global_store_dwordx4 v9, v[200:203], s[70:71]
	s_waitcnt lgkmcnt(0)
	v_mul_f32_e32 v184, v184, v144
	v_mul_f32_e32 v185, v185, v145
	v_mul_f32_e32 v186, v186, v146
	v_mul_f32_e32 v187, v187, v147
	v_mul_f32_e32 v188, v188, v148
	v_mul_f32_e32 v189, v189, v149
	v_mul_f32_e32 v190, v190, v150
	v_mul_f32_e32 v191, v191, v151
	v_cvt_pk_bf16_f32 v204, v184, v185
	v_cvt_pk_bf16_f32 v205, v186, v187
	v_cvt_pk_bf16_f32 v206, v188, v189
	v_cvt_pk_bf16_f32 v207, v190, v191
	v_add_u32_e32 v9, 0x8000, v9
	global_store_dwordx4 v9, v[204:207], s[70:71]
.Lmy_cv1_no3b:
	s_waitcnt vmcnt(34)
	s_waitcnt lgkmcnt(0)
	ds_write_b32 v2, v32 offset:0
	ds_write_b32 v2, v33 offset:264
	ds_write_b32 v2, v34 offset:528
	ds_write_b32 v2, v35 offset:792
	ds_write_b32 v2, v36 offset:1056
	ds_write_b32 v2, v37 offset:1320
	ds_write_b32 v2, v38 offset:1584
	ds_write_b32 v2, v39 offset:1848
	ds_write_b32 v2, v40 offset:2112
	ds_write_b32 v2, v41 offset:2376
	ds_write_b32 v2, v42 offset:2640
	ds_write_b32 v2, v43 offset:2904
	ds_write_b32 v2, v44 offset:3168
	ds_write_b32 v2, v45 offset:3432
	ds_write_b32 v2, v46 offset:3696
	ds_write_b32 v2, v47 offset:3960
	ds_write_b32 v2, v48 offset:4224
	ds_write_b32 v2, v49 offset:4488
	ds_write_b32 v2, v50 offset:4752
	ds_write_b32 v2, v51 offset:5016
	ds_write_b32 v2, v52 offset:5280
	ds_write_b32 v2, v53 offset:5544
	ds_write_b32 v2, v54 offset:5808
	ds_write_b32 v2, v55 offset:6072
	ds_write_b32 v2, v56 offset:6336
	ds_write_b32 v2, v57 offset:6600
	ds_write_b32 v2, v58 offset:6864
	ds_write_b32 v2, v59 offset:7128
	ds_write_b32 v2, v60 offset:7392
	ds_write_b32 v2, v61 offset:7656
	ds_write_b32 v2, v62 offset:7920
	ds_write_b32 v2, v63 offset:8184
	s_lshr_b32 s70, s5, 2
	s_lshl_b32 s70, s70, 8
	s_and_b32 s71, s5, 3
	s_lshl_b32 s71, s71, 5
	s_add_i32 s70, s70, s71
	s_add_i32 s70, s70, s54
	s_lshl_b32 s70, s70, 12
	s_lshl_b32 s71, s4, 7
	s_add_i32 s70, s70, s71
	s_add_u32 s70, s70, 0x2200000
	s_add_u32 s70, s26, s70
	s_addc_u32 s71, s27, 0
	s_waitcnt lgkmcnt(0)
	ds_read_b32 v160, v3 offset:0
	ds_read_b32 v161, v3 offset:132
	ds_read_b32 v162, v3 offset:264
	ds_read_b32 v163, v3 offset:396
	ds_read_b32 v164, v3 offset:528
	ds_read_b32 v165, v3 offset:660
	ds_read_b32 v166, v3 offset:792
	ds_read_b32 v167, v3 offset:924
	ds_read_b32 v168, v3 offset:32
	ds_read_b32 v169, v3 offset:164
	ds_read_b32 v170, v3 offset:296
	ds_read_b32 v171, v3 offset:428
	ds_read_b32 v172, v3 offset:560
	ds_read_b32 v173, v3 offset:692
	ds_read_b32 v174, v3 offset:824
	ds_read_b32 v175, v3 offset:956
	s_waitcnt lgkmcnt(8)
	v_mul_f32_e32 v160, v160, v96
	v_mul_f32_e32 v161, v161, v97
	v_mul_f32_e32 v162, v162, v98
	v_mul_f32_e32 v163, v163, v99
	v_mul_f32_e32 v164, v164, v100
	v_mul_f32_e32 v165, v165, v101
	v_mul_f32_e32 v166, v166, v102
	v_mul_f32_e32 v167, v167, v103
	v_cvt_pk_bf16_f32 v192, v160, v161
	v_cvt_pk_bf16_f32 v193, v162, v163
	v_cvt_pk_bf16_f32 v194, v164, v165
	v_cvt_pk_bf16_f32 v195, v166, v167
	v_mov_b32_e32 v9, v4
	global_store_dwordx4 v9, v[192:195], s[70:71]
	s_waitcnt lgkmcnt(0)
	v_mul_f32_e32 v168, v168, v96
	v_mul_f32_e32 v169, v169, v97
	v_mul_f32_e32 v170, v170, v98
	v_mul_f32_e32 v171, v171, v99
	v_mul_f32_e32 v172, v172, v100
	v_mul_f32_e32 v173, v173, v101
	v_mul_f32_e32 v174, v174, v102
	v_mul_f32_e32 v175, v175, v103
	v_cvt_pk_bf16_f32 v196, v168, v169
	v_cvt_pk_bf16_f32 v197, v170, v171
	v_cvt_pk_bf16_f32 v198, v172, v173
	v_cvt_pk_bf16_f32 v199, v174, v175
	v_add_u32_e32 v9, 0x8000, v9
	global_store_dwordx4 v9, v[196:199], s[70:71]
	ds_read_b32 v176, v3 offset:64
	ds_read_b32 v177, v3 offset:196
	ds_read_b32 v178, v3 offset:328
	ds_read_b32 v179, v3 offset:460
	ds_read_b32 v180, v3 offset:592
	ds_read_b32 v181, v3 offset:724
	ds_read_b32 v182, v3 offset:856
	ds_read_b32 v183, v3 offset:988
	ds_read_b32 v184, v3 offset:96
	ds_read_b32 v185, v3 offset:228
	ds_read_b32 v186, v3 offset:360
	ds_read_b32 v187, v3 offset:492
	ds_read_b32 v188, v3 offset:624
	ds_read_b32 v189, v3 offset:756
	ds_read_b32 v190, v3 offset:888
	ds_read_b32 v191, v3 offset:1020
	s_waitcnt lgkmcnt(8)
	v_mul_f32_e32 v176, v176, v96
	v_mul_f32_e32 v177, v177, v97
	v_mul_f32_e32 v178, v178, v98
	v_mul_f32_e32 v179, v179, v99
	v_mul_f32_e32 v180, v180, v100
	v_mul_f32_e32 v181, v181, v101
	v_mul_f32_e32 v182, v182, v102
	v_mul_f32_e32 v183, v183, v103
	v_cvt_pk_bf16_f32 v200, v176, v177
	v_cvt_pk_bf16_f32 v201, v178, v179
	v_cvt_pk_bf16_f32 v202, v180, v181
	v_cvt_pk_bf16_f32 v203, v182, v183
	v_add_u32_e32 v9, 0x8000, v9
	global_store_dwordx4 v9, v[200:203], s[70:71]
	s_waitcnt lgkmcnt(0)
	v_mul_f32_e32 v184, v184, v96
	v_mul_f32_e32 v185, v185, v97
	v_mul_f32_e32 v186, v186, v98
	v_mul_f32_e32 v187, v187, v99
	v_mul_f32_e32 v188, v188, v100
	v_mul_f32_e32 v189, v189, v101
	v_mul_f32_e32 v190, v190, v102
	v_mul_f32_e32 v191, v191, v103
	v_cvt_pk_bf16_f32 v204, v184, v185
	v_cvt_pk_bf16_f32 v205, v186, v187
	v_cvt_pk_bf16_f32 v206, v188, v189
	v_cvt_pk_bf16_f32 v207, v190, v191
	v_add_u32_e32 v9, 0x8000, v9
	global_store_dwordx4 v9, v[204:207], s[70:71]
	s_waitcnt vmcnt(0)
	s_waitcnt lgkmcnt(0)
	ds_write_b32 v2, v64 offset:0
	ds_write_b32 v2, v65 offset:264
	ds_write_b32 v2, v66 offset:528
	ds_write_b32 v2, v67 offset:792
	ds_write_b32 v2, v68 offset:1056
	ds_write_b32 v2, v69 offset:1320
	ds_write_b32 v2, v70 offset:1584
	ds_write_b32 v2, v71 offset:1848
	ds_write_b32 v2, v72 offset:2112
	ds_write_b32 v2, v73 offset:2376
	ds_write_b32 v2, v74 offset:2640
	ds_write_b32 v2, v75 offset:2904
	ds_write_b32 v2, v76 offset:3168
	ds_write_b32 v2, v77 offset:3432
	ds_write_b32 v2, v78 offset:3696
	ds_write_b32 v2, v79 offset:3960
	ds_write_b32 v2, v80 offset:4224
	ds_write_b32 v2, v81 offset:4488
	ds_write_b32 v2, v82 offset:4752
	ds_write_b32 v2, v83 offset:5016
	ds_write_b32 v2, v84 offset:5280
	ds_write_b32 v2, v85 offset:5544
	ds_write_b32 v2, v86 offset:5808
	ds_write_b32 v2, v87 offset:6072
	ds_write_b32 v2, v88 offset:6336
	ds_write_b32 v2, v89 offset:6600
	ds_write_b32 v2, v90 offset:6864
	ds_write_b32 v2, v91 offset:7128
	ds_write_b32 v2, v92 offset:7392
	ds_write_b32 v2, v93 offset:7656
	ds_write_b32 v2, v94 offset:7920
	ds_write_b32 v2, v95 offset:8184
	s_lshr_b32 s70, s67, 2
	s_lshl_b32 s70, s70, 8
	s_and_b32 s71, s67, 3
	s_lshl_b32 s71, s71, 5
	s_add_i32 s70, s70, s71
	s_add_i32 s70, s70, s40
	s_lshl_b32 s70, s70, 12
	s_lshl_b32 s71, s55, 7
	s_add_i32 s70, s70, s71
	s_add_u32 s70, s70, 0x2200000
	s_add_u32 s70, s26, s70
	s_addc_u32 s71, s27, 0
	s_waitcnt lgkmcnt(0)
	ds_read_b32 v160, v3 offset:0
	ds_read_b32 v161, v3 offset:132
	ds_read_b32 v162, v3 offset:264
	ds_read_b32 v163, v3 offset:396
	ds_read_b32 v164, v3 offset:528
	ds_read_b32 v165, v3 offset:660
	ds_read_b32 v166, v3 offset:792
	ds_read_b32 v167, v3 offset:924
	ds_read_b32 v168, v3 offset:32
	ds_read_b32 v169, v3 offset:164
	ds_read_b32 v170, v3 offset:296
	ds_read_b32 v171, v3 offset:428
	ds_read_b32 v172, v3 offset:560
	ds_read_b32 v173, v3 offset:692
	ds_read_b32 v174, v3 offset:824
	ds_read_b32 v175, v3 offset:956
	s_waitcnt lgkmcnt(8)
	v_mul_f32_e32 v160, v160, v104
	v_mul_f32_e32 v161, v161, v105
	v_mul_f32_e32 v162, v162, v106
	v_mul_f32_e32 v163, v163, v107
	v_mul_f32_e32 v164, v164, v108
	v_mul_f32_e32 v165, v165, v109
	v_mul_f32_e32 v166, v166, v110
	v_mul_f32_e32 v167, v167, v111
	v_cvt_pk_bf16_f32 v192, v160, v161
	v_cvt_pk_bf16_f32 v193, v162, v163
	v_cvt_pk_bf16_f32 v194, v164, v165
	v_cvt_pk_bf16_f32 v195, v166, v167
	v_mov_b32_e32 v9, v4
	global_store_dwordx4 v9, v[192:195], s[70:71]
	s_waitcnt lgkmcnt(0)
	v_mul_f32_e32 v168, v168, v104
	v_mul_f32_e32 v169, v169, v105
	v_mul_f32_e32 v170, v170, v106
	v_mul_f32_e32 v171, v171, v107
	v_mul_f32_e32 v172, v172, v108
	v_mul_f32_e32 v173, v173, v109
	v_mul_f32_e32 v174, v174, v110
	v_mul_f32_e32 v175, v175, v111
	v_cvt_pk_bf16_f32 v196, v168, v169
	v_cvt_pk_bf16_f32 v197, v170, v171
	v_cvt_pk_bf16_f32 v198, v172, v173
	v_cvt_pk_bf16_f32 v199, v174, v175
	v_add_u32_e32 v9, 0x8000, v9
	global_store_dwordx4 v9, v[196:199], s[70:71]
	ds_read_b32 v176, v3 offset:64
	ds_read_b32 v177, v3 offset:196
	ds_read_b32 v178, v3 offset:328
	ds_read_b32 v179, v3 offset:460
	ds_read_b32 v180, v3 offset:592
	ds_read_b32 v181, v3 offset:724
	ds_read_b32 v182, v3 offset:856
	ds_read_b32 v183, v3 offset:988
	ds_read_b32 v184, v3 offset:96
	ds_read_b32 v185, v3 offset:228
	ds_read_b32 v186, v3 offset:360
	ds_read_b32 v187, v3 offset:492
	ds_read_b32 v188, v3 offset:624
	ds_read_b32 v189, v3 offset:756
	ds_read_b32 v190, v3 offset:888
	ds_read_b32 v191, v3 offset:1020
	s_waitcnt lgkmcnt(8)
	v_mul_f32_e32 v176, v176, v104
	v_mul_f32_e32 v177, v177, v105
	v_mul_f32_e32 v178, v178, v106
	v_mul_f32_e32 v179, v179, v107
	v_mul_f32_e32 v180, v180, v108
	v_mul_f32_e32 v181, v181, v109
	v_mul_f32_e32 v182, v182, v110
	v_mul_f32_e32 v183, v183, v111
	v_cvt_pk_bf16_f32 v200, v176, v177
	v_cvt_pk_bf16_f32 v201, v178, v179
	v_cvt_pk_bf16_f32 v202, v180, v181
	v_cvt_pk_bf16_f32 v203, v182, v183
	v_add_u32_e32 v9, 0x8000, v9
	global_store_dwordx4 v9, v[200:203], s[70:71]
	s_waitcnt lgkmcnt(0)
	v_mul_f32_e32 v184, v184, v104
	v_mul_f32_e32 v185, v185, v105
	v_mul_f32_e32 v186, v186, v106
	v_mul_f32_e32 v187, v187, v107
	v_mul_f32_e32 v188, v188, v108
	v_mul_f32_e32 v189, v189, v109
	v_mul_f32_e32 v190, v190, v110
	v_mul_f32_e32 v191, v191, v111
	v_cvt_pk_bf16_f32 v204, v184, v185
	v_cvt_pk_bf16_f32 v205, v186, v187
	v_cvt_pk_bf16_f32 v206, v188, v189
	v_cvt_pk_bf16_f32 v207, v190, v191
	v_add_u32_e32 v9, 0x8000, v9
	global_store_dwordx4 v9, v[204:207], s[70:71]
	s_waitcnt vmcnt(0) lgkmcnt(0)

.LBB0_475:
	s_cmp_gt_u32 s29, 4
	s_cselect_b64 s[0:1], -1, 0
	s_and_b64 s[0:1], s[36:37], s[0:1]
	s_andn2_b64 vcc, exec, s[0:1]
	s_cbranch_vccnz .LBB0_525
	s_waitcnt vmcnt(0)
	v_cmp_eq_u32_e32 vcc, 0, v208
	s_waitcnt vmcnt(0) lgkmcnt(0)
	s_barrier
	v_readfirstlane_b32 s3, v208
	s_nop 3
	s_lshr_b32 s3, s3, 6
	s_cmp_eq_u32 s3, 0
	s_cbranch_scc1 .Lmy_cv2_end
	v_readlane_b32 s36, v237, 0
	v_readlane_b32 s37, v237, 1
	s_mul_i32 s4, s2, 7
	s_add_i32 s4, s4, s3
	s_add_i32 s4, s4, -1
	s_lshl_b32 s72, s3, 14
	s_mov_b32 s3, s4
	s_nop 4
	s_load_dwordx4 s[60:63], s[36:37], 0x60
	s_load_dwordx2 s[64:65], s[36:37], 0x70
	v_lshrrev_b32_e32 v6, 5, v209
	v_and_b32_e32 v7, 31, v209
	v_mul_u32_u24_e32 v0, 0x1600, v6
	v_add_lshl_u32 v0, v0, v7, 2
	v_lshlrev_b32_e32 v152, 11, v6
	v_add_lshl_u32 v152, v152, v7, 2
	v_mul_u32_u24_e32 v2, 33, v6
	v_add_lshl_u32 v2, v2, v7, 2
	v_add_u32_e32 v2, s72, v2
	v_and_b32_e32 v8, 7, v209
	v_lshrrev_b32_e32 v9, 3, v209
	v_mul_u32_u24_e32 v3, 0x108, v8
	v_add_lshl_u32 v3, v3, v9, 2
	v_add_u32_e32 v3, s72, v3
	v_lshlrev_b32_e32 v4, 12, v9
	v_lshl_add_u32 v4, v8, 4, v4
	v_lshlrev_b32_e32 v5, 5, v8
	s_waitcnt lgkmcnt(0)
	s_add_i32 s66, s3, 7680
	s_cmpk_ge_u32 s66, 0x1600
	s_cselect_b32 s68, s64, s62
	s_cselect_b32 s69, s65, s63
	s_cselect_b32 s54, 128, 0
	s_cselect_b32 s41, 0x1600, 0
	s_sub_u32 s41, s66, s41
	s_mul_hi_u32 s4, s41, 0xba2e8ba3
	s_lshr_b32 s4, s4, 7
	s_mul_i32 s70, s4, 0xb0
	s_sub_u32 s5, s41, s70
	s_mul_i32 s70, s4, 0x160000
	s_lshl_b32 s71, s5, 7
	s_add_u32 s68, s68, s70
	s_addc_u32 s69, s69, 0
	s_add_u32 s68, s68, s71
	s_addc_u32 s69, s69, 0
	v_mov_b32_e32 v1, v0
	global_load_dword v32, v1, s[68:69] nt
	v_add_u32_e32 v1, 0xb000, v1
	global_load_dword v33, v1, s[68:69] nt
	v_add_u32_e32 v1, 0xb000, v1
	global_load_dword v34, v1, s[68:69] nt
	v_add_u32_e32 v1, 0xb000, v1
	global_load_dword v35, v1, s[68:69] nt
	v_add_u32_e32 v1, 0xb000, v1
	global_load_dword v36, v1, s[68:69] nt
	v_add_u32_e32 v1, 0xb000, v1
	global_load_dword v37, v1, s[68:69] nt
	v_add_u32_e32 v1, 0xb000, v1
	global_load_dword v38, v1, s[68:69] nt
	v_add_u32_e32 v1, 0xb000, v1
	global_load_dword v39, v1, s[68:69] nt
	v_add_u32_e32 v1, 0xb000, v1
	global_load_dword v40, v1, s[68:69] nt
	v_add_u32_e32 v1, 0xb000, v1
	global_load_dword v41, v1, s[68:69] nt
	v_add_u32_e32 v1, 0xb000, v1
	global_load_dword v42, v1, s[68:69] nt
	v_add_u32_e32 v1, 0xb000, v1
	global_load_dword v43, v1, s[68:69] nt
	v_add_u32_e32 v1, 0xb000, v1
	global_load_dword v44, v1, s[68:69] nt
	v_add_u32_e32 v1, 0xb000, v1
	global_load_dword v45, v1, s[68:69] nt
	v_add_u32_e32 v1, 0xb000, v1
	global_load_dword v46, v1, s[68:69] nt
	v_add_u32_e32 v1, 0xb000, v1
	global_load_dword v47, v1, s[68:69] nt
	v_add_u32_e32 v1, 0xb000, v1
	global_load_dword v48, v1, s[68:69] nt
	v_add_u32_e32 v1, 0xb000, v1
	global_load_dword v49, v1, s[68:69] nt
	v_add_u32_e32 v1, 0xb000, v1
	global_load_dword v50, v1, s[68:69] nt
	v_add_u32_e32 v1, 0xb000, v1
	global_load_dword v51, v1, s[68:69] nt
	v_add_u32_e32 v1, 0xb000, v1
	global_load_dword v52, v1, s[68:69] nt
	v_add_u32_e32 v1, 0xb000, v1
	global_load_dword v53, v1, s[68:69] nt
	v_add_u32_e32 v1, 0xb000, v1
	global_load_dword v54, v1, s[68:69] nt
	v_add_u32_e32 v1, 0xb000, v1
	global_load_dword v55, v1, s[68:69] nt
	v_add_u32_e32 v1, 0xb000, v1
	global_load_dword v56, v1, s[68:69] nt
	v_add_u32_e32 v1, 0xb000, v1
	global_load_dword v57, v1, s[68:69] nt
	v_add_u32_e32 v1, 0xb000, v1
	global_load_dword v58, v1, s[68:69] nt
	v_add_u32_e32 v1, 0xb000, v1
	global_load_dword v59, v1, s[68:69] nt
	v_add_u32_e32 v1, 0xb000, v1
	global_load_dword v60, v1, s[68:69] nt
	v_add_u32_e32 v1, 0xb000, v1
	global_load_dword v61, v1, s[68:69] nt
	v_add_u32_e32 v1, 0xb000, v1
	global_load_dword v62, v1, s[68:69] nt
	v_add_u32_e32 v1, 0xb000, v1
	global_load_dword v63, v1, s[68:69] nt
	s_lshl_b32 s70, s4, 8
	s_add_u32 s70, s60, s70
	s_addc_u32 s71, s61, 0
	global_load_dwordx4 v[96:99], v5, s[70:71]
	global_load_dwordx4 v[100:103], v5, s[70:71] offset:16
	s_addk_i32 s66, 0x700
	s_cmpk_ge_u32 s66, 0x1600
	s_cselect_b32 s68, s64, s62
	s_cselect_b32 s69, s65, s63
	s_cselect_b32 s40, 128, 0
	s_cselect_b32 s41, 0x1600, 0
	s_sub_u32 s41, s66, s41
	s_mul_hi_u32 s55, s41, 0xba2e8ba3
	s_lshr_b32 s55, s55, 7
	s_mul_i32 s70, s55, 0xb0
	s_sub_u32 s67, s41, s70
	s_mul_i32 s70, s55, 0x160000
	s_lshl_b32 s71, s67, 7
	s_add_u32 s68, s68, s70
	s_addc_u32 s69, s69, 0
	s_add_u32 s68, s68, s71
	s_addc_u32 s69, s69, 0
	v_mov_b32_e32 v1, v0
	global_load_dword v64, v1, s[68:69] nt
	v_add_u32_e32 v1, 0xb000, v1
	global_load_dword v65, v1, s[68:69] nt
	v_add_u32_e32 v1, 0xb000, v1
	global_load_dword v66, v1, s[68:69] nt
	v_add_u32_e32 v1, 0xb000, v1
	global_load_dword v67, v1, s[68:69] nt
	v_add_u32_e32 v1, 0xb000, v1
	global_load_dword v68, v1, s[68:69] nt
	v_add_u32_e32 v1, 0xb000, v1
	global_load_dword v69, v1, s[68:69] nt
	v_add_u32_e32 v1, 0xb000, v1
	global_load_dword v70, v1, s[68:69] nt
	v_add_u32_e32 v1, 0xb000, v1
	global_load_dword v71, v1, s[68:69] nt
	v_add_u32_e32 v1, 0xb000, v1
	global_load_dword v72, v1, s[68:69] nt
	v_add_u32_e32 v1, 0xb000, v1
	global_load_dword v73, v1, s[68:69] nt
	v_add_u32_e32 v1, 0xb000, v1
	global_load_dword v74, v1, s[68:69] nt
	v_add_u32_e32 v1, 0xb000, v1
	global_load_dword v75, v1, s[68:69] nt
	v_add_u32_e32 v1, 0xb000, v1
	global_load_dword v76, v1, s[68:69] nt
	v_add_u32_e32 v1, 0xb000, v1
	global_load_dword v77, v1, s[68:69] nt
	v_add_u32_e32 v1, 0xb000, v1
	global_load_dword v78, v1, s[68:69] nt
	v_add_u32_e32 v1, 0xb000, v1
	global_load_dword v79, v1, s[68:69] nt
	v_add_u32_e32 v1, 0xb000, v1
	global_load_dword v80, v1, s[68:69] nt
	v_add_u32_e32 v1, 0xb000, v1
	global_load_dword v81, v1, s[68:69] nt
	v_add_u32_e32 v1, 0xb000, v1
	global_load_dword v82, v1, s[68:69] nt
	v_add_u32_e32 v1, 0xb000, v1
	global_load_dword v83, v1, s[68:69] nt
	v_add_u32_e32 v1, 0xb000, v1
	global_load_dword v84, v1, s[68:69] nt
	v_add_u32_e32 v1, 0xb000, v1
	global_load_dword v85, v1, s[68:69] nt
	v_add_u32_e32 v1, 0xb000, v1
	global_load_dword v86, v1, s[68:69] nt
	v_add_u32_e32 v1, 0xb000, v1
	global_load_dword v87, v1, s[68:69] nt
	v_add_u32_e32 v1, 0xb000, v1
	global_load_dword v88, v1, s[68:69] nt
	v_add_u32_e32 v1, 0xb000, v1
	global_load_dword v89, v1, s[68:69] nt
	v_add_u32_e32 v1, 0xb000, v1
	global_load_dword v90, v1, s[68:69] nt
	v_add_u32_e32 v1, 0xb000, v1
	global_load_dword v91, v1, s[68:69] nt
	v_add_u32_e32 v1, 0xb000, v1
	global_load_dword v92, v1, s[68:69] nt
	v_add_u32_e32 v1, 0xb000, v1
	global_load_dword v93, v1, s[68:69] nt
	v_add_u32_e32 v1, 0xb000, v1
	global_load_dword v94, v1, s[68:69] nt
	v_add_u32_e32 v1, 0xb000, v1
	global_load_dword v95, v1, s[68:69] nt
	s_lshl_b32 s70, s55, 8
	s_add_u32 s70, s60, s70
	s_addc_u32 s71, s61, 0
	global_load_dwordx4 v[104:107], v5, s[70:71]
	global_load_dwordx4 v[108:111], v5, s[70:71] offset:16
	s_waitcnt vmcnt(34)
	s_waitcnt lgkmcnt(0)
	ds_write_b32 v2, v32 offset:0
	ds_write_b32 v2, v33 offset:264
	ds_write_b32 v2, v34 offset:528
	ds_write_b32 v2, v35 offset:792
	ds_write_b32 v2, v36 offset:1056
	ds_write_b32 v2, v37 offset:1320
	ds_write_b32 v2, v38 offset:1584
	ds_write_b32 v2, v39 offset:1848
	ds_write_b32 v2, v40 offset:2112
	ds_write_b32 v2, v41 offset:2376
	ds_write_b32 v2, v42 offset:2640
	ds_write_b32 v2, v43 offset:2904
	ds_write_b32 v2, v44 offset:3168
	ds_write_b32 v2, v45 offset:3432
	ds_write_b32 v2, v46 offset:3696
	ds_write_b32 v2, v47 offset:3960
	ds_write_b32 v2, v48 offset:4224
	ds_write_b32 v2, v49 offset:4488
	ds_write_b32 v2, v50 offset:4752
	ds_write_b32 v2, v51 offset:5016
	ds_write_b32 v2, v52 offset:5280
	ds_write_b32 v2, v53 offset:5544
	ds_write_b32 v2, v54 offset:5808
	ds_write_b32 v2, v55 offset:6072
	ds_write_b32 v2, v56 offset:6336
	ds_write_b32 v2, v57 offset:6600
	ds_write_b32 v2, v58 offset:6864
	ds_write_b32 v2, v59 offset:7128
	ds_write_b32 v2, v60 offset:7392
	ds_write_b32 v2, v61 offset:7656
	ds_write_b32 v2, v62 offset:7920
	ds_write_b32 v2, v63 offset:8184
	s_lshr_b32 s70, s5, 2
	s_lshl_b32 s70, s70, 8
	s_and_b32 s71, s5, 3
	s_lshl_b32 s71, s71, 5
	s_add_i32 s70, s70, s71
	s_add_i32 s70, s70, s54
	s_lshl_b32 s70, s70, 12
	s_lshl_b32 s71, s4, 7
	s_add_i32 s70, s70, s71
	s_add_u32 s70, s70, 0x2200000
	s_add_u32 s70, s26, s70
	s_addc_u32 s71, s27, 0
	s_waitcnt lgkmcnt(0)
	ds_read_b32 v160, v3 offset:0
	ds_read_b32 v161, v3 offset:132
	ds_read_b32 v162, v3 offset:264
	ds_read_b32 v163, v3 offset:396
	ds_read_b32 v164, v3 offset:528
	ds_read_b32 v165, v3 offset:660
	ds_read_b32 v166, v3 offset:792
	ds_read_b32 v167, v3 offset:924
	ds_read_b32 v168, v3 offset:32
	ds_read_b32 v169, v3 offset:164
	ds_read_b32 v170, v3 offset:296
	ds_read_b32 v171, v3 offset:428
	ds_read_b32 v172, v3 offset:560
	ds_read_b32 v173, v3 offset:692
	ds_read_b32 v174, v3 offset:824
	ds_read_b32 v175, v3 offset:956
	s_waitcnt lgkmcnt(8)
	v_mul_f32_e32 v160, v160, v96
	v_mul_f32_e32 v161, v161, v97
	v_mul_f32_e32 v162, v162, v98
	v_mul_f32_e32 v163, v163, v99
	v_mul_f32_e32 v164, v164, v100
	v_mul_f32_e32 v165, v165, v101
	v_mul_f32_e32 v166, v166, v102
	v_mul_f32_e32 v167, v167, v103
	v_cvt_pk_bf16_f32 v192, v160, v161
	v_cvt_pk_bf16_f32 v193, v162, v163
	v_cvt_pk_bf16_f32 v194, v164, v165
	v_cvt_pk_bf16_f32 v195, v166, v167
	v_mov_b32_e32 v9, v4
	global_store_dwordx4 v9, v[192:195], s[70:71]
	s_waitcnt lgkmcnt(0)
	v_mul_f32_e32 v168, v168, v96
	v_mul_f32_e32 v169, v169, v97
	v_mul_f32_e32 v170, v170, v98
	v_mul_f32_e32 v171, v171, v99
	v_mul_f32_e32 v172, v172, v100
	v_mul_f32_e32 v173, v173, v101
	v_mul_f32_e32 v174, v174, v102
	v_mul_f32_e32 v175, v175, v103
	v_cvt_pk_bf16_f32 v196, v168, v169
	v_cvt_pk_bf16_f32 v197, v170, v171
	v_cvt_pk_bf16_f32 v198, v172, v173
	v_cvt_pk_bf16_f32 v199, v174, v175
	v_add_u32_e32 v9, 0x8000, v9
	global_store_dwordx4 v9, v[196:199], s[70:71]
	ds_read_b32 v176, v3 offset:64
	ds_read_b32 v177, v3 offset:196
	ds_read_b32 v178, v3 offset:328
	ds_read_b32 v179, v3 offset:460
	ds_read_b32 v180, v3 offset:592
	ds_read_b32 v181, v3 offset:724
	ds_read_b32 v182, v3 offset:856
	ds_read_b32 v183, v3 offset:988
	ds_read_b32 v184, v3 offset:96
	ds_read_b32 v185, v3 offset:228
	ds_read_b32 v186, v3 offset:360
	ds_read_b32 v187, v3 offset:492
	ds_read_b32 v188, v3 offset:624
	ds_read_b32 v189, v3 offset:756
	ds_read_b32 v190, v3 offset:888
	ds_read_b32 v191, v3 offset:1020
	s_waitcnt lgkmcnt(8)
	v_mul_f32_e32 v176, v176, v96
	v_mul_f32_e32 v177, v177, v97
	v_mul_f32_e32 v178, v178, v98
	v_mul_f32_e32 v179, v179, v99
	v_mul_f32_e32 v180, v180, v100
	v_mul_f32_e32 v181, v181, v101
	v_mul_f32_e32 v182, v182, v102
	v_mul_f32_e32 v183, v183, v103
	v_cvt_pk_bf16_f32 v200, v176, v177
	v_cvt_pk_bf16_f32 v201, v178, v179
	v_cvt_pk_bf16_f32 v202, v180, v181
	v_cvt_pk_bf16_f32 v203, v182, v183
	v_add_u32_e32 v9, 0x8000, v9
	global_store_dwordx4 v9, v[200:203], s[70:71]
	s_waitcnt lgkmcnt(0)
	v_mul_f32_e32 v184, v184, v96
	v_mul_f32_e32 v185, v185, v97
	v_mul_f32_e32 v186, v186, v98
	v_mul_f32_e32 v187, v187, v99
	v_mul_f32_e32 v188, v188, v100
	v_mul_f32_e32 v189, v189, v101
	v_mul_f32_e32 v190, v190, v102
	v_mul_f32_e32 v191, v191, v103
	v_cvt_pk_bf16_f32 v204, v184, v185
	v_cvt_pk_bf16_f32 v205, v186, v187
	v_cvt_pk_bf16_f32 v206, v188, v189
	v_cvt_pk_bf16_f32 v207, v190, v191
	v_add_u32_e32 v9, 0x8000, v9
	global_store_dwordx4 v9, v[204:207], s[70:71]
	s_waitcnt vmcnt(0)
	s_waitcnt lgkmcnt(0)
	ds_write_b32 v2, v64 offset:0
	ds_write_b32 v2, v65 offset:264
	ds_write_b32 v2, v66 offset:528
	ds_write_b32 v2, v67 offset:792
	ds_write_b32 v2, v68 offset:1056
	ds_write_b32 v2, v69 offset:1320
	ds_write_b32 v2, v70 offset:1584
	ds_write_b32 v2, v71 offset:1848
	ds_write_b32 v2, v72 offset:2112
	ds_write_b32 v2, v73 offset:2376
	ds_write_b32 v2, v74 offset:2640
	ds_write_b32 v2, v75 offset:2904
	ds_write_b32 v2, v76 offset:3168
	ds_write_b32 v2, v77 offset:3432
	ds_write_b32 v2, v78 offset:3696
	ds_write_b32 v2, v79 offset:3960
	ds_write_b32 v2, v80 offset:4224
	ds_write_b32 v2, v81 offset:4488
	ds_write_b32 v2, v82 offset:4752
	ds_write_b32 v2, v83 offset:5016
	ds_write_b32 v2, v84 offset:5280
	ds_write_b32 v2, v85 offset:5544
	ds_write_b32 v2, v86 offset:5808
	ds_write_b32 v2, v87 offset:6072
	ds_write_b32 v2, v88 offset:6336
	ds_write_b32 v2, v89 offset:6600
	ds_write_b32 v2, v90 offset:6864
	ds_write_b32 v2, v91 offset:7128
	ds_write_b32 v2, v92 offset:7392
	ds_write_b32 v2, v93 offset:7656
	ds_write_b32 v2, v94 offset:7920
	ds_write_b32 v2, v95 offset:8184
	s_lshr_b32 s70, s67, 2
	s_lshl_b32 s70, s70, 8
	s_and_b32 s71, s67, 3
	s_lshl_b32 s71, s71, 5
	s_add_i32 s70, s70, s71
	s_add_i32 s70, s70, s40
	s_lshl_b32 s70, s70, 12
	s_lshl_b32 s71, s55, 7
	s_add_i32 s70, s70, s71
	s_add_u32 s70, s70, 0x2200000
	s_add_u32 s70, s26, s70
	s_addc_u32 s71, s27, 0
	s_waitcnt lgkmcnt(0)
	ds_read_b32 v160, v3 offset:0
	ds_read_b32 v161, v3 offset:132
	ds_read_b32 v162, v3 offset:264
	ds_read_b32 v163, v3 offset:396
	ds_read_b32 v164, v3 offset:528
	ds_read_b32 v165, v3 offset:660
	ds_read_b32 v166, v3 offset:792
	ds_read_b32 v167, v3 offset:924
	ds_read_b32 v168, v3 offset:32
	ds_read_b32 v169, v3 offset:164
	ds_read_b32 v170, v3 offset:296
	ds_read_b32 v171, v3 offset:428
	ds_read_b32 v172, v3 offset:560
	ds_read_b32 v173, v3 offset:692
	ds_read_b32 v174, v3 offset:824
	ds_read_b32 v175, v3 offset:956
	s_waitcnt lgkmcnt(8)
	v_mul_f32_e32 v160, v160, v104
	v_mul_f32_e32 v161, v161, v105
	v_mul_f32_e32 v162, v162, v106
	v_mul_f32_e32 v163, v163, v107
	v_mul_f32_e32 v164, v164, v108
	v_mul_f32_e32 v165, v165, v109
	v_mul_f32_e32 v166, v166, v110
	v_mul_f32_e32 v167, v167, v111
	v_cvt_pk_bf16_f32 v192, v160, v161
	v_cvt_pk_bf16_f32 v193, v162, v163
	v_cvt_pk_bf16_f32 v194, v164, v165
	v_cvt_pk_bf16_f32 v195, v166, v167
	v_mov_b32_e32 v9, v4
	global_store_dwordx4 v9, v[192:195], s[70:71]
	s_waitcnt lgkmcnt(0)
	v_mul_f32_e32 v168, v168, v104
	v_mul_f32_e32 v169, v169, v105
	v_mul_f32_e32 v170, v170, v106
	v_mul_f32_e32 v171, v171, v107
	v_mul_f32_e32 v172, v172, v108
	v_mul_f32_e32 v173, v173, v109
	v_mul_f32_e32 v174, v174, v110
	v_mul_f32_e32 v175, v175, v111
	v_cvt_pk_bf16_f32 v196, v168, v169
	v_cvt_pk_bf16_f32 v197, v170, v171
	v_cvt_pk_bf16_f32 v198, v172, v173
	v_cvt_pk_bf16_f32 v199, v174, v175
	v_add_u32_e32 v9, 0x8000, v9
	global_store_dwordx4 v9, v[196:199], s[70:71]
	ds_read_b32 v176, v3 offset:64
	ds_read_b32 v177, v3 offset:196
	ds_read_b32 v178, v3 offset:328
	ds_read_b32 v179, v3 offset:460
	ds_read_b32 v180, v3 offset:592
	ds_read_b32 v181, v3 offset:724
	ds_read_b32 v182, v3 offset:856
	ds_read_b32 v183, v3 offset:988
	ds_read_b32 v184, v3 offset:96
	ds_read_b32 v185, v3 offset:228
	ds_read_b32 v186, v3 offset:360
	ds_read_b32 v187, v3 offset:492
	ds_read_b32 v188, v3 offset:624
	ds_read_b32 v189, v3 offset:756
	ds_read_b32 v190, v3 offset:888
	ds_read_b32 v191, v3 offset:1020
	s_waitcnt lgkmcnt(8)
	v_mul_f32_e32 v176, v176, v104
	v_mul_f32_e32 v177, v177, v105
	v_mul_f32_e32 v178, v178, v106
	v_mul_f32_e32 v179, v179, v107
	v_mul_f32_e32 v180, v180, v108
	v_mul_f32_e32 v181, v181, v109
	v_mul_f32_e32 v182, v182, v110
	v_mul_f32_e32 v183, v183, v111
	v_cvt_pk_bf16_f32 v200, v176, v177
	v_cvt_pk_bf16_f32 v201, v178, v179
	v_cvt_pk_bf16_f32 v202, v180, v181
	v_cvt_pk_bf16_f32 v203, v182, v183
	v_add_u32_e32 v9, 0x8000, v9
	global_store_dwordx4 v9, v[200:203], s[70:71]
	s_waitcnt lgkmcnt(0)
	v_mul_f32_e32 v184, v184, v104
	v_mul_f32_e32 v185, v185, v105
	v_mul_f32_e32 v186, v186, v106
	v_mul_f32_e32 v187, v187, v107
	v_mul_f32_e32 v188, v188, v108
	v_mul_f32_e32 v189, v189, v109
	v_mul_f32_e32 v190, v190, v110
	v_mul_f32_e32 v191, v191, v111
	v_cvt_pk_bf16_f32 v204, v184, v185
	v_cvt_pk_bf16_f32 v205, v186, v187
	v_cvt_pk_bf16_f32 v206, v188, v189
	v_cvt_pk_bf16_f32 v207, v190, v191
	v_add_u32_e32 v9, 0x8000, v9
	global_store_dwordx4 v9, v[204:207], s[70:71]
	s_waitcnt vmcnt(0) lgkmcnt(0)
